# EpiResid XB stores write-through (sc1): less dirty L2 to write back at the following grid barrier
# baseline (speedup 1.0000x reference)
; __device__ __forceinline__ float bf_lo(unsigned u) { return __uint_as_float(u << 16); }
; __device__ __forceinline__ float bf_hi(unsigned u) { return __uint_as_float(u & 0xffff0000u); }
; __device__ __forceinline__ unsigned pk_bf16(float lo, float hi) { const f32x2 v = {lo, hi}; const bf16x2_t b = __builtin_convertvector(v, bf16x2_t); return __builtin_bit_cast(unsigned, b); }
;     __device__ __forceinline__ void operator()(const f32x4 (&acc)[2][2][4][2], const pg8::Unit& u, int wr, int wc, int fr, int fq) const {
;     ...
;         const int row0 = u.pm * 256 + wr * 64 + fr, col0 = u.pn * 256 + wc * 32 + 4 * fq;
;         const bool rf32 = (rp != nullptr) && (u.pm < MP / 256);
; #pragma unroll
;         for (int ai = 0; ai < 2; ++ai)
; #pragma unroll
;             for (int m = 0; m < 4; ++m) {
;                 const int row = row0 + ai * 128 + m * 16; const size_t off = (size_t)row * DM + col0; float q = 0.f;
;                 f32x4 r4[2][2];
;                 if (rf32) {
; #pragma unroll
;                     for (int bj = 0; bj < 2; ++bj)
; #pragma unroll
;                         for (int n = 0; n < 2; ++n) r4[bj][n] = *(const f32x4*)(rp + off + bj * 128 + n * 16);
;                 } else {
; #pragma unroll
;                     for (int bj = 0; bj < 2; ++bj)
; #pragma unroll
;                         for (int n = 0; n < 2; ++n) { const u32x2 w = *(const u32x2*)(XB + off + bj * 128 + n * 16); r4[bj][n] = (f32x4){bf_lo(w.x), bf_hi(w.x), bf_lo(w.y), bf_hi(w.y)}; }
;                 }
; #pragma unroll
;                 for (int bj = 0; bj < 2; ++bj)
; #pragma unroll
;                     for (int n = 0; n < 2; ++n) { const f32x4 x4 = r4[bj][n] + acc[ai][bj][m][n];
;                         q += (x4[0] * x4[0] + x4[1] * x4[1]) + (x4[2] * x4[2] + x4[3] * x4[3]);
;                         u32x2 w; w.x = pk_bf16(x4[0], x4[1]); w.y = pk_bf16(x4[2], x4[3]); *(u32x2*)(XB + off + bj * 128 + n * 16) = w; }
;                 q += __shfl_xor(q, 16); q += __shfl_xor(q, 32);
;                 if (fq == 0) ssq[(size_t)row * 16 + u.pn * 4 + wc] = q;
.LBB0_1683:
	s_lshl_b32 s4, s51, 8
	v_mov_b32_e32 v158, v1
	s_add_i32 s4, s4, s46
	s_lshl_b32 s28, s50, 2
	v_add_u32_e32 v160, s4, v158
	v_ashrrev_i32_e32 v161, 31, v160
	v_lshl_or_b32 v158, s50, 8, v163
	v_lshlrev_b64 v[166:167], 11, v[160:161]
	v_ashrrev_i32_e32 v159, 31, v158
	v_lshl_add_u64 v[166:167], s[14:15], 0, v[166:167]
	v_lshl_add_u64 v[166:167], v[158:159], 1, v[166:167]
	s_ashr_i32 s29, s28, 31
	v_lshlrev_b32_e32 v252, 11, v160
	v_lshl_add_u32 v252, v158, 1, v252
	v_bfe_u32 v253, v190, 4, 1
	v_mul_u32_u24_e32 v253, 24, v253
	v_add_u32_e32 v252, v252, v253
	s_lshl_b32 s88, s45, 2
	v_lshl_add_u32 v189, v160, 6, s88
	v_lshl_add_u32 v189, s28, 2, v189
	global_load_dwordx4 v[204:207], v252, s[14:15]
	global_load_dwordx4 v[208:211], v252, s[14:15] offset:256
	v_add_u32_e32 v253, 0x8000, v252
	global_load_dwordx4 v[212:215], v253, s[14:15]
	global_load_dwordx4 v[216:219], v253, s[14:15] offset:256
	v_add_u32_e32 v253, 0x10000, v252
	global_load_dwordx4 v[220:223], v253, s[14:15]
	global_load_dwordx4 v[224:227], v253, s[14:15] offset:256
	v_add_u32_e32 v253, 0x18000, v252
	global_load_dwordx4 v[228:231], v253, s[14:15]
	global_load_dwordx4 v[232:235], v253, s[14:15] offset:256
	v_add_u32_e32 v253, 0x40000, v252
	global_load_dwordx4 v[236:239], v253, s[14:15]
	global_load_dwordx4 v[240:243], v253, s[14:15] offset:256
	v_add_u32_e32 v253, 0x48000, v252
	global_load_dwordx4 v[244:247], v253, s[14:15]
	global_load_dwordx4 v[248:251], v253, s[14:15] offset:256
	s_waitcnt vmcnt(10)
	v_permlane16_swap_b32_e32 v204, v206
	v_permlane16_swap_b32_e32 v205, v207
	v_permlane16_swap_b32_e32 v208, v210
	v_permlane16_swap_b32_e32 v209, v211
	v_lshlrev_b32_e32 v166, 16, v204
	v_and_b32_e32 v167, 0xffff0000, v204
	v_lshlrev_b32_e32 v168, 16, v205
	v_and_b32_e32 v169, 0xffff0000, v205
	v_lshlrev_b32_e32 v170, 16, v206
	v_and_b32_e32 v171, 0xffff0000, v206
	v_lshlrev_b32_e32 v172, 16, v207
	v_and_b32_e32 v173, 0xffff0000, v207
	v_lshlrev_b32_e32 v174, 16, v208
	v_and_b32_e32 v175, 0xffff0000, v208
	v_lshlrev_b32_e32 v176, 16, v209
	v_and_b32_e32 v177, 0xffff0000, v209
	v_lshlrev_b32_e32 v178, 16, v210
	v_and_b32_e32 v179, 0xffff0000, v210
	v_lshlrev_b32_e32 v180, 16, v211
	v_and_b32_e32 v181, 0xffff0000, v211
	v_pk_add_f32 v[126:127], v[126:127], v[166:167]
	v_pk_add_f32 v[128:129], v[128:129], v[168:169]
	v_pk_add_f32 v[122:123], v[122:123], v[170:171]
	v_pk_add_f32 v[124:125], v[124:125], v[172:173]
	v_pk_add_f32 v[118:119], v[118:119], v[174:175]
	v_pk_add_f32 v[120:121], v[120:121], v[176:177]
	v_pk_add_f32 v[114:115], v[114:115], v[178:179]
	v_pk_add_f32 v[116:117], v[116:117], v[180:181]
	v_add_u32_e32 v253, 0x50000, v252
	global_load_dwordx4 v[204:207], v253, s[14:15]
	global_load_dwordx4 v[208:211], v253, s[14:15] offset:256
	v_cvt_pk_bf16_f32 v166, v126, v127
	v_cvt_pk_bf16_f32 v167, v128, v129
	v_cvt_pk_bf16_f32 v168, v122, v123
	v_cvt_pk_bf16_f32 v169, v124, v125
	v_cvt_pk_bf16_f32 v170, v118, v119
	v_cvt_pk_bf16_f32 v171, v120, v121
	v_cvt_pk_bf16_f32 v172, v114, v115
	v_cvt_pk_bf16_f32 v173, v116, v117
	v_mul_f32_e32 v174, v126, v126
	v_mul_f32_e32 v175, v122, v122
	v_mul_f32_e32 v176, v118, v118
	v_mul_f32_e32 v177, v114, v114
	v_fmac_f32_e32 v174, v127, v127
	v_fmac_f32_e32 v175, v123, v123
	v_fmac_f32_e32 v176, v119, v119
	v_fmac_f32_e32 v177, v115, v115
	v_fmac_f32_e32 v174, v128, v128
	v_fmac_f32_e32 v175, v124, v124
	v_fmac_f32_e32 v176, v120, v120
	v_fmac_f32_e32 v177, v116, v116
	v_fmac_f32_e32 v174, v129, v129
	v_fmac_f32_e32 v175, v125, v125
	v_fmac_f32_e32 v176, v121, v121
	v_fmac_f32_e32 v177, v117, v117
	v_add_f32_e32 v174, v174, v175
	v_add_f32_e32 v176, v176, v177
	v_add_f32_e32 v178, v174, v176
	v_mov_b32_e32 v179, v178
	v_permlane16_swap_b32_e32 v166, v168
	v_permlane16_swap_b32_e32 v167, v169
	v_permlane32_swap_b32_e32 v179, v178
	v_permlane16_swap_b32_e32 v170, v172
	v_permlane16_swap_b32_e32 v171, v173
	global_store_dwordx4 v252, v[166:169], s[14:15] sc1
	global_store_dwordx4 v252, v[170:173], s[14:15] offset:256 sc1
	v_add_f32_e32 v178, v178, v179
	v_mov_b32_e32 v179, v178
	s_nop 0
	s_nop 0
	v_permlane16_swap_b32_e32 v179, v178
	v_add_f32_e32 v178, v178, v179
	s_and_saveexec_b64 s[30:31], s[8:9]
	global_store_dword v189, v178, s[16:17]
	s_or_b64 exec, exec, s[30:31]
	s_waitcnt vmcnt(12)
; __device__ __forceinline__ float bf_lo(unsigned u) { return __uint_as_float(u << 16); }
; __device__ __forceinline__ float bf_hi(unsigned u) { return __uint_as_float(u & 0xffff0000u); }
; __device__ __forceinline__ unsigned pk_bf16(float lo, float hi) { const f32x2 v = {lo, hi}; const bf16x2_t b = __builtin_convertvector(v, bf16x2_t); return __builtin_bit_cast(unsigned, b); }
;     __device__ __forceinline__ void operator()(const f32x4 (&acc)[2][2][4][2], const pg8::Unit& u, int wr, int wc, int fr, int fq) const {
;     ...
;                     for (int bj = 0; bj < 2; ++bj)
; #pragma unroll
;                         for (int n = 0; n < 2; ++n) { const u32x2 w = *(const u32x2*)(XB + off + bj * 128 + n * 16); r4[bj][n] = (f32x4){bf_lo(w.x), bf_hi(w.x), bf_lo(w.y), bf_hi(w.y)}; }
;                 }
; #pragma unroll
;                 for (int bj = 0; bj < 2; ++bj)
; #pragma unroll
;                     for (int n = 0; n < 2; ++n) { const f32x4 x4 = r4[bj][n] + acc[ai][bj][m][n];
;                         q += (x4[0] * x4[0] + x4[1] * x4[1]) + (x4[2] * x4[2] + x4[3] * x4[3]);
;                         u32x2 w; w.x = pk_bf16(x4[0], x4[1]); w.y = pk_bf16(x4[2], x4[3]); *(u32x2*)(XB + off + bj * 128 + n * 16) = w; }
;                 q += __shfl_xor(q, 16); q += __shfl_xor(q, 32);
;                 if (fq == 0) ssq[(size_t)row * 16 + u.pn * 4 + wc] = q;
	v_permlane16_swap_b32_e32 v212, v214
	v_permlane16_swap_b32_e32 v213, v215
	v_permlane16_swap_b32_e32 v216, v218
	v_permlane16_swap_b32_e32 v217, v219
	v_lshlrev_b32_e32 v166, 16, v212
	v_and_b32_e32 v167, 0xffff0000, v212
	v_lshlrev_b32_e32 v168, 16, v213
	v_and_b32_e32 v169, 0xffff0000, v213
	v_lshlrev_b32_e32 v170, 16, v214
	v_and_b32_e32 v171, 0xffff0000, v214
	v_lshlrev_b32_e32 v172, 16, v215
	v_and_b32_e32 v173, 0xffff0000, v215
	v_lshlrev_b32_e32 v174, 16, v216
	v_and_b32_e32 v175, 0xffff0000, v216
	v_lshlrev_b32_e32 v176, 16, v217
	v_and_b32_e32 v177, 0xffff0000, v217
	v_lshlrev_b32_e32 v178, 16, v218
	v_and_b32_e32 v179, 0xffff0000, v218
	v_lshlrev_b32_e32 v180, 16, v219
	v_and_b32_e32 v181, 0xffff0000, v219
	v_pk_add_f32 v[110:111], v[110:111], v[166:167]
	v_pk_add_f32 v[112:113], v[112:113], v[168:169]
	v_pk_add_f32 v[106:107], v[106:107], v[170:171]
	v_pk_add_f32 v[108:109], v[108:109], v[172:173]
	v_pk_add_f32 v[102:103], v[102:103], v[174:175]
	v_pk_add_f32 v[104:105], v[104:105], v[176:177]
	v_pk_add_f32 v[98:99], v[98:99], v[178:179]
	v_pk_add_f32 v[100:101], v[100:101], v[180:181]
	v_add_u32_e32 v253, 0x58000, v252
	global_load_dwordx4 v[212:215], v253, s[14:15]
	global_load_dwordx4 v[216:219], v253, s[14:15] offset:256
	v_cvt_pk_bf16_f32 v166, v110, v111
	v_cvt_pk_bf16_f32 v167, v112, v113
	v_cvt_pk_bf16_f32 v168, v106, v107
	v_cvt_pk_bf16_f32 v169, v108, v109
	v_cvt_pk_bf16_f32 v170, v102, v103
	v_cvt_pk_bf16_f32 v171, v104, v105
	v_cvt_pk_bf16_f32 v172, v98, v99
	v_cvt_pk_bf16_f32 v173, v100, v101
	v_mul_f32_e32 v174, v110, v110
	v_mul_f32_e32 v175, v106, v106
	v_mul_f32_e32 v176, v102, v102
	v_mul_f32_e32 v177, v98, v98
	v_fmac_f32_e32 v174, v111, v111
	v_fmac_f32_e32 v175, v107, v107
	v_fmac_f32_e32 v176, v103, v103
	v_fmac_f32_e32 v177, v99, v99
	v_fmac_f32_e32 v174, v112, v112
	v_fmac_f32_e32 v175, v108, v108
	v_fmac_f32_e32 v176, v104, v104
	v_fmac_f32_e32 v177, v100, v100
	v_fmac_f32_e32 v174, v113, v113
	v_fmac_f32_e32 v175, v109, v109
	v_fmac_f32_e32 v176, v105, v105
	v_fmac_f32_e32 v177, v101, v101
	v_add_f32_e32 v174, v174, v175
	v_add_f32_e32 v176, v176, v177
	v_add_f32_e32 v178, v174, v176
	v_mov_b32_e32 v179, v178
	v_permlane16_swap_b32_e32 v166, v168
	v_permlane16_swap_b32_e32 v167, v169
	v_permlane32_swap_b32_e32 v179, v178
	v_permlane16_swap_b32_e32 v170, v172
	v_permlane16_swap_b32_e32 v171, v173
	v_add_u32_e32 v253, 0x8000, v252
	global_store_dwordx4 v253, v[166:169], s[14:15] sc1
	global_store_dwordx4 v253, v[170:173], s[14:15] offset:256 sc1
	v_add_f32_e32 v178, v178, v179
	v_mov_b32_e32 v179, v178
	s_nop 0
	s_nop 0
	v_permlane16_swap_b32_e32 v179, v178
	v_add_f32_e32 v178, v178, v179
	s_and_saveexec_b64 s[30:31], s[8:9]
	global_store_dword v189, v178, s[16:17] offset:1024
	s_or_b64 exec, exec, s[30:31]
	s_waitcnt vmcnt(14)
	v_permlane16_swap_b32_e32 v220, v222
	v_permlane16_swap_b32_e32 v221, v223
	v_permlane16_swap_b32_e32 v224, v226
	v_permlane16_swap_b32_e32 v225, v227
	v_lshlrev_b32_e32 v166, 16, v220
	v_and_b32_e32 v167, 0xffff0000, v220
	v_lshlrev_b32_e32 v168, 16, v221
	v_and_b32_e32 v169, 0xffff0000, v221
	v_lshlrev_b32_e32 v170, 16, v222
	v_and_b32_e32 v171, 0xffff0000, v222
	v_lshlrev_b32_e32 v172, 16, v223
	v_and_b32_e32 v173, 0xffff0000, v223
	v_lshlrev_b32_e32 v174, 16, v224
	v_and_b32_e32 v175, 0xffff0000, v224
	v_lshlrev_b32_e32 v176, 16, v225
	v_and_b32_e32 v177, 0xffff0000, v225
	v_lshlrev_b32_e32 v178, 16, v226
	v_and_b32_e32 v179, 0xffff0000, v226
	v_lshlrev_b32_e32 v180, 16, v227
	v_and_b32_e32 v181, 0xffff0000, v227
	v_pk_add_f32 v[94:95], v[94:95], v[166:167]
	v_pk_add_f32 v[96:97], v[96:97], v[168:169]
	v_pk_add_f32 v[90:91], v[90:91], v[170:171]
	v_pk_add_f32 v[92:93], v[92:93], v[172:173]
	v_pk_add_f32 v[86:87], v[86:87], v[174:175]
	v_pk_add_f32 v[88:89], v[88:89], v[176:177]
	v_pk_add_f32 v[82:83], v[82:83], v[178:179]
	v_pk_add_f32 v[84:85], v[84:85], v[180:181]
	v_cvt_pk_bf16_f32 v166, v94, v95
	v_cvt_pk_bf16_f32 v167, v96, v97
	v_cvt_pk_bf16_f32 v168, v90, v91
	v_cvt_pk_bf16_f32 v169, v92, v93
	v_cvt_pk_bf16_f32 v170, v86, v87
	v_cvt_pk_bf16_f32 v171, v88, v89
	v_cvt_pk_bf16_f32 v172, v82, v83
	v_cvt_pk_bf16_f32 v173, v84, v85
	v_mul_f32_e32 v174, v94, v94
	v_mul_f32_e32 v175, v90, v90
	v_mul_f32_e32 v176, v86, v86
	v_mul_f32_e32 v177, v82, v82
	v_fmac_f32_e32 v174, v95, v95
	v_fmac_f32_e32 v175, v91, v91
	v_fmac_f32_e32 v176, v87, v87
	v_fmac_f32_e32 v177, v83, v83
	v_fmac_f32_e32 v174, v96, v96
	v_fmac_f32_e32 v175, v92, v92
	v_fmac_f32_e32 v176, v88, v88
	v_fmac_f32_e32 v177, v84, v84
	v_fmac_f32_e32 v174, v97, v97
	v_fmac_f32_e32 v175, v93, v93
	v_fmac_f32_e32 v176, v89, v89
	v_fmac_f32_e32 v177, v85, v85
	v_add_f32_e32 v174, v174, v175
	v_add_f32_e32 v176, v176, v177
	v_add_f32_e32 v178, v174, v176
	v_mov_b32_e32 v179, v178
	v_permlane16_swap_b32_e32 v166, v168
	v_permlane16_swap_b32_e32 v167, v169
	v_permlane32_swap_b32_e32 v179, v178
	v_permlane16_swap_b32_e32 v170, v172
	v_permlane16_swap_b32_e32 v171, v173
	v_add_u32_e32 v253, 0x10000, v252
	global_store_dwordx4 v253, v[166:169], s[14:15] sc1
	global_store_dwordx4 v253, v[170:173], s[14:15] offset:256 sc1
	v_add_f32_e32 v178, v178, v179
	v_mov_b32_e32 v179, v178
	s_nop 0
	s_nop 0
	v_permlane16_swap_b32_e32 v179, v178
	v_add_f32_e32 v178, v178, v179
	s_and_saveexec_b64 s[30:31], s[8:9]
	global_store_dword v189, v178, s[16:17] offset:2048
	s_or_b64 exec, exec, s[30:31]
	s_waitcnt vmcnt(14)
; __device__ __forceinline__ float bf_lo(unsigned u) { return __uint_as_float(u << 16); }
; __device__ __forceinline__ float bf_hi(unsigned u) { return __uint_as_float(u & 0xffff0000u); }
; __device__ __forceinline__ unsigned pk_bf16(float lo, float hi) { const f32x2 v = {lo, hi}; const bf16x2_t b = __builtin_convertvector(v, bf16x2_t); return __builtin_bit_cast(unsigned, b); }
;     __device__ __forceinline__ void operator()(const f32x4 (&acc)[2][2][4][2], const pg8::Unit& u, int wr, int wc, int fr, int fq) const {
;     ...
;                     for (int bj = 0; bj < 2; ++bj)
; #pragma unroll
;                         for (int n = 0; n < 2; ++n) { const u32x2 w = *(const u32x2*)(XB + off + bj * 128 + n * 16); r4[bj][n] = (f32x4){bf_lo(w.x), bf_hi(w.x), bf_lo(w.y), bf_hi(w.y)}; }
;                 }
; #pragma unroll
;                 for (int bj = 0; bj < 2; ++bj)
; #pragma unroll
;                     for (int n = 0; n < 2; ++n) { const f32x4 x4 = r4[bj][n] + acc[ai][bj][m][n];
;                         q += (x4[0] * x4[0] + x4[1] * x4[1]) + (x4[2] * x4[2] + x4[3] * x4[3]);
;                         u32x2 w; w.x = pk_bf16(x4[0], x4[1]); w.y = pk_bf16(x4[2], x4[3]); *(u32x2*)(XB + off + bj * 128 + n * 16) = w; }
;                 q += __shfl_xor(q, 16); q += __shfl_xor(q, 32);
;                 if (fq == 0) ssq[(size_t)row * 16 + u.pn * 4 + wc] = q;
	v_permlane16_swap_b32_e32 v228, v230
	v_permlane16_swap_b32_e32 v229, v231
	v_permlane16_swap_b32_e32 v232, v234
	v_permlane16_swap_b32_e32 v233, v235
	v_lshlrev_b32_e32 v166, 16, v228
	v_and_b32_e32 v167, 0xffff0000, v228
	v_lshlrev_b32_e32 v168, 16, v229
	v_and_b32_e32 v169, 0xffff0000, v229
	v_lshlrev_b32_e32 v170, 16, v230
	v_and_b32_e32 v171, 0xffff0000, v230
	v_lshlrev_b32_e32 v172, 16, v231
	v_and_b32_e32 v173, 0xffff0000, v231
	v_lshlrev_b32_e32 v174, 16, v232
	v_and_b32_e32 v175, 0xffff0000, v232
	v_lshlrev_b32_e32 v176, 16, v233
	v_and_b32_e32 v177, 0xffff0000, v233
	v_lshlrev_b32_e32 v178, 16, v234
	v_and_b32_e32 v179, 0xffff0000, v234
	v_lshlrev_b32_e32 v180, 16, v235
	v_and_b32_e32 v181, 0xffff0000, v235
	v_pk_add_f32 v[78:79], v[78:79], v[166:167]
	v_pk_add_f32 v[80:81], v[80:81], v[168:169]
	v_pk_add_f32 v[74:75], v[74:75], v[170:171]
	v_pk_add_f32 v[76:77], v[76:77], v[172:173]
	v_pk_add_f32 v[70:71], v[70:71], v[174:175]
	v_pk_add_f32 v[72:73], v[72:73], v[176:177]
	v_pk_add_f32 v[66:67], v[66:67], v[178:179]
	v_pk_add_f32 v[68:69], v[68:69], v[180:181]
	v_cvt_pk_bf16_f32 v166, v78, v79
	v_cvt_pk_bf16_f32 v167, v80, v81
	v_cvt_pk_bf16_f32 v168, v74, v75
	v_cvt_pk_bf16_f32 v169, v76, v77
	v_cvt_pk_bf16_f32 v170, v70, v71
	v_cvt_pk_bf16_f32 v171, v72, v73
	v_cvt_pk_bf16_f32 v172, v66, v67
	v_cvt_pk_bf16_f32 v173, v68, v69
	v_mul_f32_e32 v174, v78, v78
	v_mul_f32_e32 v175, v74, v74
	v_mul_f32_e32 v176, v70, v70
	v_mul_f32_e32 v177, v66, v66
	v_fmac_f32_e32 v174, v79, v79
	v_fmac_f32_e32 v175, v75, v75
	v_fmac_f32_e32 v176, v71, v71
	v_fmac_f32_e32 v177, v67, v67
	v_fmac_f32_e32 v174, v80, v80
	v_fmac_f32_e32 v175, v76, v76
	v_fmac_f32_e32 v176, v72, v72
	v_fmac_f32_e32 v177, v68, v68
	v_fmac_f32_e32 v174, v81, v81
	v_fmac_f32_e32 v175, v77, v77
	v_fmac_f32_e32 v176, v73, v73
	v_fmac_f32_e32 v177, v69, v69
	v_add_f32_e32 v174, v174, v175
	v_add_f32_e32 v176, v176, v177
	v_add_f32_e32 v178, v174, v176
	v_mov_b32_e32 v179, v178
	v_permlane16_swap_b32_e32 v166, v168
	v_permlane16_swap_b32_e32 v167, v169
	v_permlane32_swap_b32_e32 v179, v178
	v_permlane16_swap_b32_e32 v170, v172
	v_permlane16_swap_b32_e32 v171, v173
	v_add_u32_e32 v253, 0x18000, v252
	global_store_dwordx4 v253, v[166:169], s[14:15] sc1
	global_store_dwordx4 v253, v[170:173], s[14:15] offset:256 sc1
	v_add_f32_e32 v178, v178, v179
	v_mov_b32_e32 v179, v178
	s_nop 0
	s_nop 0
	v_permlane16_swap_b32_e32 v179, v178
	v_add_f32_e32 v178, v178, v179
	s_and_saveexec_b64 s[30:31], s[8:9]
	global_store_dword v189, v178, s[16:17] offset:3072
	s_or_b64 exec, exec, s[30:31]
	s_waitcnt vmcnt(14)
	v_permlane16_swap_b32_e32 v236, v238
	v_permlane16_swap_b32_e32 v237, v239
	v_permlane16_swap_b32_e32 v240, v242
	v_permlane16_swap_b32_e32 v241, v243
	v_lshlrev_b32_e32 v166, 16, v236
	v_and_b32_e32 v167, 0xffff0000, v236
	v_lshlrev_b32_e32 v168, 16, v237
	v_and_b32_e32 v169, 0xffff0000, v237
	v_lshlrev_b32_e32 v170, 16, v238
	v_and_b32_e32 v171, 0xffff0000, v238
	v_lshlrev_b32_e32 v172, 16, v239
	v_and_b32_e32 v173, 0xffff0000, v239
	v_lshlrev_b32_e32 v174, 16, v240
	v_and_b32_e32 v175, 0xffff0000, v240
	v_lshlrev_b32_e32 v176, 16, v241
	v_and_b32_e32 v177, 0xffff0000, v241
	v_lshlrev_b32_e32 v178, 16, v242
	v_and_b32_e32 v179, 0xffff0000, v242
	v_lshlrev_b32_e32 v180, 16, v243
	v_and_b32_e32 v181, 0xffff0000, v243
	v_pk_add_f32 v[62:63], v[62:63], v[166:167]
	v_pk_add_f32 v[64:65], v[64:65], v[168:169]
	v_pk_add_f32 v[58:59], v[58:59], v[170:171]
	v_pk_add_f32 v[60:61], v[60:61], v[172:173]
	v_pk_add_f32 v[54:55], v[54:55], v[174:175]
	v_pk_add_f32 v[56:57], v[56:57], v[176:177]
	v_pk_add_f32 v[50:51], v[50:51], v[178:179]
	v_pk_add_f32 v[52:53], v[52:53], v[180:181]
	v_cvt_pk_bf16_f32 v166, v62, v63
	v_cvt_pk_bf16_f32 v167, v64, v65
	v_cvt_pk_bf16_f32 v168, v58, v59
	v_cvt_pk_bf16_f32 v169, v60, v61
	v_cvt_pk_bf16_f32 v170, v54, v55
	v_cvt_pk_bf16_f32 v171, v56, v57
	v_cvt_pk_bf16_f32 v172, v50, v51
	v_cvt_pk_bf16_f32 v173, v52, v53
	v_mul_f32_e32 v174, v62, v62
	v_mul_f32_e32 v175, v58, v58
	v_mul_f32_e32 v176, v54, v54
	v_mul_f32_e32 v177, v50, v50
	v_fmac_f32_e32 v174, v63, v63
	v_fmac_f32_e32 v175, v59, v59
	v_fmac_f32_e32 v176, v55, v55
	v_fmac_f32_e32 v177, v51, v51
	v_fmac_f32_e32 v174, v64, v64
	v_fmac_f32_e32 v175, v60, v60
	v_fmac_f32_e32 v176, v56, v56
	v_fmac_f32_e32 v177, v52, v52
	v_fmac_f32_e32 v174, v65, v65
	v_fmac_f32_e32 v175, v61, v61
	v_fmac_f32_e32 v176, v57, v57
	v_fmac_f32_e32 v177, v53, v53
	v_add_f32_e32 v174, v174, v175
	v_add_f32_e32 v176, v176, v177
	v_add_f32_e32 v178, v174, v176
	v_mov_b32_e32 v179, v178
	v_permlane16_swap_b32_e32 v166, v168
	v_permlane16_swap_b32_e32 v167, v169
	v_permlane32_swap_b32_e32 v179, v178
	v_permlane16_swap_b32_e32 v170, v172
	v_permlane16_swap_b32_e32 v171, v173
	v_add_u32_e32 v253, 0x40000, v252
	global_store_dwordx4 v253, v[166:169], s[14:15] sc1
	global_store_dwordx4 v253, v[170:173], s[14:15] offset:256 sc1
	v_add_f32_e32 v178, v178, v179
	v_mov_b32_e32 v179, v178
	v_add_u32_e32 v189, 0x2000, v189
	s_nop 0
	v_permlane16_swap_b32_e32 v179, v178
	v_add_f32_e32 v178, v178, v179
	s_and_saveexec_b64 s[30:31], s[8:9]
	global_store_dword v189, v178, s[16:17]
	s_or_b64 exec, exec, s[30:31]
	s_waitcnt vmcnt(14)
; __device__ __forceinline__ float bf_lo(unsigned u) { return __uint_as_float(u << 16); }
; __device__ __forceinline__ float bf_hi(unsigned u) { return __uint_as_float(u & 0xffff0000u); }
; __device__ __forceinline__ unsigned pk_bf16(float lo, float hi) { const f32x2 v = {lo, hi}; const bf16x2_t b = __builtin_convertvector(v, bf16x2_t); return __builtin_bit_cast(unsigned, b); }
;     __device__ __forceinline__ void operator()(const f32x4 (&acc)[2][2][4][2], const pg8::Unit& u, int wr, int wc, int fr, int fq) const {
;     ...
;                     for (int bj = 0; bj < 2; ++bj)
; #pragma unroll
;                         for (int n = 0; n < 2; ++n) { const u32x2 w = *(const u32x2*)(XB + off + bj * 128 + n * 16); r4[bj][n] = (f32x4){bf_lo(w.x), bf_hi(w.x), bf_lo(w.y), bf_hi(w.y)}; }
;                 }
; #pragma unroll
;                 for (int bj = 0; bj < 2; ++bj)
; #pragma unroll
;                     for (int n = 0; n < 2; ++n) { const f32x4 x4 = r4[bj][n] + acc[ai][bj][m][n];
;                         q += (x4[0] * x4[0] + x4[1] * x4[1]) + (x4[2] * x4[2] + x4[3] * x4[3]);
;                         u32x2 w; w.x = pk_bf16(x4[0], x4[1]); w.y = pk_bf16(x4[2], x4[3]); *(u32x2*)(XB + off + bj * 128 + n * 16) = w; }
;                 q += __shfl_xor(q, 16); q += __shfl_xor(q, 32);
;                 if (fq == 0) ssq[(size_t)row * 16 + u.pn * 4 + wc] = q;
	v_permlane16_swap_b32_e32 v244, v246
	v_permlane16_swap_b32_e32 v245, v247
	v_permlane16_swap_b32_e32 v248, v250
	v_permlane16_swap_b32_e32 v249, v251
	v_lshlrev_b32_e32 v166, 16, v244
	v_and_b32_e32 v167, 0xffff0000, v244
	v_lshlrev_b32_e32 v168, 16, v245
	v_and_b32_e32 v169, 0xffff0000, v245
	v_lshlrev_b32_e32 v170, 16, v246
	v_and_b32_e32 v171, 0xffff0000, v246
	v_lshlrev_b32_e32 v172, 16, v247
	v_and_b32_e32 v173, 0xffff0000, v247
	v_lshlrev_b32_e32 v174, 16, v248
	v_and_b32_e32 v175, 0xffff0000, v248
	v_lshlrev_b32_e32 v176, 16, v249
	v_and_b32_e32 v177, 0xffff0000, v249
	v_lshlrev_b32_e32 v178, 16, v250
	v_and_b32_e32 v179, 0xffff0000, v250
	v_lshlrev_b32_e32 v180, 16, v251
	v_and_b32_e32 v181, 0xffff0000, v251
	v_pk_add_f32 v[46:47], v[46:47], v[166:167]
	v_pk_add_f32 v[48:49], v[48:49], v[168:169]
	v_pk_add_f32 v[42:43], v[42:43], v[170:171]
	v_pk_add_f32 v[44:45], v[44:45], v[172:173]
	v_pk_add_f32 v[38:39], v[38:39], v[174:175]
	v_pk_add_f32 v[40:41], v[40:41], v[176:177]
	v_pk_add_f32 v[34:35], v[34:35], v[178:179]
	v_pk_add_f32 v[36:37], v[36:37], v[180:181]
	v_cvt_pk_bf16_f32 v166, v46, v47
	v_cvt_pk_bf16_f32 v167, v48, v49
	v_cvt_pk_bf16_f32 v168, v42, v43
	v_cvt_pk_bf16_f32 v169, v44, v45
	v_cvt_pk_bf16_f32 v170, v38, v39
	v_cvt_pk_bf16_f32 v171, v40, v41
	v_cvt_pk_bf16_f32 v172, v34, v35
	v_cvt_pk_bf16_f32 v173, v36, v37
	v_mul_f32_e32 v174, v46, v46
	v_mul_f32_e32 v175, v42, v42
	v_mul_f32_e32 v176, v38, v38
	v_mul_f32_e32 v177, v34, v34
	v_fmac_f32_e32 v174, v47, v47
	v_fmac_f32_e32 v175, v43, v43
	v_fmac_f32_e32 v176, v39, v39
	v_fmac_f32_e32 v177, v35, v35
	v_fmac_f32_e32 v174, v48, v48
	v_fmac_f32_e32 v175, v44, v44
	v_fmac_f32_e32 v176, v40, v40
	v_fmac_f32_e32 v177, v36, v36
	v_fmac_f32_e32 v174, v49, v49
	v_fmac_f32_e32 v175, v45, v45
	v_fmac_f32_e32 v176, v41, v41
	v_fmac_f32_e32 v177, v37, v37
	v_add_f32_e32 v174, v174, v175
	v_add_f32_e32 v176, v176, v177
	v_add_f32_e32 v178, v174, v176
	v_mov_b32_e32 v179, v178
	v_permlane16_swap_b32_e32 v166, v168
	v_permlane16_swap_b32_e32 v167, v169
	v_permlane32_swap_b32_e32 v179, v178
	v_permlane16_swap_b32_e32 v170, v172
	v_permlane16_swap_b32_e32 v171, v173
	v_add_u32_e32 v253, 0x48000, v252
	global_store_dwordx4 v253, v[166:169], s[14:15] sc1
	global_store_dwordx4 v253, v[170:173], s[14:15] offset:256 sc1
	v_add_f32_e32 v178, v178, v179
	v_mov_b32_e32 v179, v178
	s_nop 0
	s_nop 0
	v_permlane16_swap_b32_e32 v179, v178
	v_add_f32_e32 v178, v178, v179
	s_and_saveexec_b64 s[30:31], s[8:9]
	global_store_dword v189, v178, s[16:17] offset:1024
	s_or_b64 exec, exec, s[30:31]
	s_waitcnt vmcnt(14)
; __device__ __forceinline__ float bf_lo(unsigned u) { return __uint_as_float(u << 16); }
; __device__ __forceinline__ float bf_hi(unsigned u) { return __uint_as_float(u & 0xffff0000u); }
; __device__ __forceinline__ unsigned pk_bf16(float lo, float hi) { const f32x2 v = {lo, hi}; const bf16x2_t b = __builtin_convertvector(v, bf16x2_t); return __builtin_bit_cast(unsigned, b); }
;     __device__ __forceinline__ void operator()(const f32x4 (&acc)[2][2][4][2], const pg8::Unit& u, int wr, int wc, int fr, int fq) const {
;     ...
;                     for (int bj = 0; bj < 2; ++bj)
; #pragma unroll
;                         for (int n = 0; n < 2; ++n) { const u32x2 w = *(const u32x2*)(XB + off + bj * 128 + n * 16); r4[bj][n] = (f32x4){bf_lo(w.x), bf_hi(w.x), bf_lo(w.y), bf_hi(w.y)}; }
;                 }
; #pragma unroll
;                 for (int bj = 0; bj < 2; ++bj)
; #pragma unroll
;                     for (int n = 0; n < 2; ++n) { const f32x4 x4 = r4[bj][n] + acc[ai][bj][m][n];
;                         q += (x4[0] * x4[0] + x4[1] * x4[1]) + (x4[2] * x4[2] + x4[3] * x4[3]);
;                         u32x2 w; w.x = pk_bf16(x4[0], x4[1]); w.y = pk_bf16(x4[2], x4[3]); *(u32x2*)(XB + off + bj * 128 + n * 16) = w; }
;                 q += __shfl_xor(q, 16); q += __shfl_xor(q, 32);
;                 if (fq == 0) ssq[(size_t)row * 16 + u.pn * 4 + wc] = q;
	v_permlane16_swap_b32_e32 v204, v206
	v_permlane16_swap_b32_e32 v205, v207
	v_permlane16_swap_b32_e32 v208, v210
	v_permlane16_swap_b32_e32 v209, v211
	v_lshlrev_b32_e32 v166, 16, v204
	v_and_b32_e32 v167, 0xffff0000, v204
	v_lshlrev_b32_e32 v168, 16, v205
	v_and_b32_e32 v169, 0xffff0000, v205
	v_lshlrev_b32_e32 v170, 16, v206
	v_and_b32_e32 v171, 0xffff0000, v206
	v_lshlrev_b32_e32 v172, 16, v207
	v_and_b32_e32 v173, 0xffff0000, v207
	v_lshlrev_b32_e32 v174, 16, v208
	v_and_b32_e32 v175, 0xffff0000, v208
	v_lshlrev_b32_e32 v176, 16, v209
	v_and_b32_e32 v177, 0xffff0000, v209
	v_lshlrev_b32_e32 v178, 16, v210
	v_and_b32_e32 v179, 0xffff0000, v210
	v_lshlrev_b32_e32 v180, 16, v211
	v_and_b32_e32 v181, 0xffff0000, v211
	v_pk_add_f32 v[30:31], v[30:31], v[166:167]
	v_pk_add_f32 v[32:33], v[32:33], v[168:169]
	v_pk_add_f32 v[26:27], v[26:27], v[170:171]
	v_pk_add_f32 v[28:29], v[28:29], v[172:173]
	v_pk_add_f32 v[22:23], v[22:23], v[174:175]
	v_pk_add_f32 v[24:25], v[24:25], v[176:177]
	v_pk_add_f32 v[18:19], v[18:19], v[178:179]
	v_pk_add_f32 v[20:21], v[20:21], v[180:181]
	v_cvt_pk_bf16_f32 v166, v30, v31
	v_cvt_pk_bf16_f32 v167, v32, v33
	v_cvt_pk_bf16_f32 v168, v26, v27
	v_cvt_pk_bf16_f32 v169, v28, v29
	v_cvt_pk_bf16_f32 v170, v22, v23
	v_cvt_pk_bf16_f32 v171, v24, v25
	v_cvt_pk_bf16_f32 v172, v18, v19
	v_cvt_pk_bf16_f32 v173, v20, v21
	v_mul_f32_e32 v174, v30, v30
	v_mul_f32_e32 v175, v26, v26
	v_mul_f32_e32 v176, v22, v22
	v_mul_f32_e32 v177, v18, v18
	v_fmac_f32_e32 v174, v31, v31
	v_fmac_f32_e32 v175, v27, v27
	v_fmac_f32_e32 v176, v23, v23
	v_fmac_f32_e32 v177, v19, v19
	v_fmac_f32_e32 v174, v32, v32
	v_fmac_f32_e32 v175, v28, v28
	v_fmac_f32_e32 v176, v24, v24
	v_fmac_f32_e32 v177, v20, v20
	v_fmac_f32_e32 v174, v33, v33
	v_fmac_f32_e32 v175, v29, v29
	v_fmac_f32_e32 v176, v25, v25
	v_fmac_f32_e32 v177, v21, v21
	v_add_f32_e32 v174, v174, v175
	v_add_f32_e32 v176, v176, v177
	v_add_f32_e32 v178, v174, v176
	v_mov_b32_e32 v179, v178
	v_permlane16_swap_b32_e32 v166, v168
	v_permlane16_swap_b32_e32 v167, v169
	v_permlane32_swap_b32_e32 v179, v178
	v_permlane16_swap_b32_e32 v170, v172
	v_permlane16_swap_b32_e32 v171, v173
	v_add_u32_e32 v253, 0x50000, v252
	global_store_dwordx4 v253, v[166:169], s[14:15] sc1
	global_store_dwordx4 v253, v[170:173], s[14:15] offset:256 sc1
	v_add_f32_e32 v178, v178, v179
	v_mov_b32_e32 v179, v178
	s_nop 0
	s_nop 0
	v_permlane16_swap_b32_e32 v179, v178
	v_add_f32_e32 v178, v178, v179
	s_and_saveexec_b64 s[30:31], s[8:9]
	global_store_dword v189, v178, s[16:17] offset:2048
	s_or_b64 exec, exec, s[30:31]
	s_waitcnt vmcnt(12)
	v_permlane16_swap_b32_e32 v212, v214
	v_permlane16_swap_b32_e32 v213, v215
	v_permlane16_swap_b32_e32 v216, v218
	v_permlane16_swap_b32_e32 v217, v219
	v_lshlrev_b32_e32 v166, 16, v212
	v_and_b32_e32 v167, 0xffff0000, v212
	v_lshlrev_b32_e32 v168, 16, v213
	v_and_b32_e32 v169, 0xffff0000, v213
	v_lshlrev_b32_e32 v170, 16, v214
	v_and_b32_e32 v171, 0xffff0000, v214
	v_lshlrev_b32_e32 v172, 16, v215
	v_and_b32_e32 v173, 0xffff0000, v215
	v_lshlrev_b32_e32 v174, 16, v216
	v_and_b32_e32 v175, 0xffff0000, v216
	v_lshlrev_b32_e32 v176, 16, v217
	v_and_b32_e32 v177, 0xffff0000, v217
	v_lshlrev_b32_e32 v178, 16, v218
	v_and_b32_e32 v179, 0xffff0000, v218
	v_lshlrev_b32_e32 v180, 16, v219
	v_and_b32_e32 v181, 0xffff0000, v219
	v_pk_add_f32 v[14:15], v[14:15], v[166:167]
	v_pk_add_f32 v[16:17], v[16:17], v[168:169]
	v_pk_add_f32 v[10:11], v[10:11], v[170:171]
	v_pk_add_f32 v[12:13], v[12:13], v[172:173]
	v_pk_add_f32 v[6:7], v[6:7], v[174:175]
	v_pk_add_f32 v[8:9], v[8:9], v[176:177]
	v_pk_add_f32 v[2:3], v[2:3], v[178:179]
	v_pk_add_f32 v[4:5], v[4:5], v[180:181]
	v_cvt_pk_bf16_f32 v166, v14, v15
	v_cvt_pk_bf16_f32 v167, v16, v17
	v_cvt_pk_bf16_f32 v168, v10, v11
	v_cvt_pk_bf16_f32 v169, v12, v13
	v_cvt_pk_bf16_f32 v170, v6, v7
	v_cvt_pk_bf16_f32 v171, v8, v9
	v_cvt_pk_bf16_f32 v172, v2, v3
	v_cvt_pk_bf16_f32 v173, v4, v5
	v_mul_f32_e32 v174, v14, v14
	v_mul_f32_e32 v175, v10, v10
	v_mul_f32_e32 v176, v6, v6
	v_mul_f32_e32 v177, v2, v2
	v_fmac_f32_e32 v174, v15, v15
	v_fmac_f32_e32 v175, v11, v11
	v_fmac_f32_e32 v176, v7, v7
	v_fmac_f32_e32 v177, v3, v3
	v_fmac_f32_e32 v174, v16, v16
	v_fmac_f32_e32 v175, v12, v12
	v_fmac_f32_e32 v176, v8, v8
	v_fmac_f32_e32 v177, v4, v4
	v_fmac_f32_e32 v174, v17, v17
	v_fmac_f32_e32 v175, v13, v13
	v_fmac_f32_e32 v176, v9, v9
	v_fmac_f32_e32 v177, v5, v5
	v_add_f32_e32 v174, v174, v175
	v_add_f32_e32 v176, v176, v177
	v_add_f32_e32 v178, v174, v176
	v_mov_b32_e32 v179, v178
	v_permlane16_swap_b32_e32 v166, v168
	v_permlane16_swap_b32_e32 v167, v169
	v_permlane32_swap_b32_e32 v179, v178
	v_permlane16_swap_b32_e32 v170, v172
	v_permlane16_swap_b32_e32 v171, v173
	v_add_u32_e32 v253, 0x58000, v252
	global_store_dwordx4 v253, v[166:169], s[14:15] sc1
	global_store_dwordx4 v253, v[170:173], s[14:15] offset:256 sc1
	v_add_f32_e32 v178, v178, v179
	v_mov_b32_e32 v179, v178
	s_nop 0
	s_nop 0
	v_permlane16_swap_b32_e32 v179, v178
	v_add_f32_e32 v178, v178, v179
	s_and_saveexec_b64 s[30:31], s[8:9]
	global_store_dword v189, v178, s[16:17] offset:3072
	s_or_b64 exec, exec, s[30:31]

; __device__ __forceinline__ float bf_lo(unsigned u) { return __uint_as_float(u << 16); }
; __device__ __forceinline__ float bf_hi(unsigned u) { return __uint_as_float(u & 0xffff0000u); }
; __device__ __forceinline__ unsigned pk_bf16(float lo, float hi) { const f32x2 v = {lo, hi}; const bf16x2_t b = __builtin_convertvector(v, bf16x2_t); return __builtin_bit_cast(unsigned, b); }
;     __device__ __forceinline__ void operator()(const f32x4 (&acc)[2][2][4][2], const pg8::Unit& u, int wr, int wc, int fr, int fq) const {
;     ...
;         const int row0 = u.pm * 256 + wr * 64 + fr, col0 = u.pn * 256 + wc * 32 + 4 * fq;
;         const bool rf32 = (rp != nullptr) && (u.pm < MP / 256);
; #pragma unroll
;         for (int ai = 0; ai < 2; ++ai)
; #pragma unroll
;             for (int m = 0; m < 4; ++m) {
;                 const int row = row0 + ai * 128 + m * 16; const size_t off = (size_t)row * DM + col0; float q = 0.f;
;                 f32x4 r4[2][2];
;                 if (rf32) {
; #pragma unroll
;                     for (int bj = 0; bj < 2; ++bj)
; #pragma unroll
;                         for (int n = 0; n < 2; ++n) r4[bj][n] = *(const f32x4*)(rp + off + bj * 128 + n * 16);
;                 } else {
; #pragma unroll
;                     for (int bj = 0; bj < 2; ++bj)
; #pragma unroll
;                         for (int n = 0; n < 2; ++n) { const u32x2 w = *(const u32x2*)(XB + off + bj * 128 + n * 16); r4[bj][n] = (f32x4){bf_lo(w.x), bf_hi(w.x), bf_lo(w.y), bf_hi(w.y)}; }
;                 }
; #pragma unroll
;                 for (int bj = 0; bj < 2; ++bj)
; #pragma unroll
;                     for (int n = 0; n < 2; ++n) { const f32x4 x4 = r4[bj][n] + acc[ai][bj][m][n];
;                         q += (x4[0] * x4[0] + x4[1] * x4[1]) + (x4[2] * x4[2] + x4[3] * x4[3]);
;                         u32x2 w; w.x = pk_bf16(x4[0], x4[1]); w.y = pk_bf16(x4[2], x4[3]); *(u32x2*)(XB + off + bj * 128 + n * 16) = w; }
;                 q += __shfl_xor(q, 16); q += __shfl_xor(q, 32);
;                 if (fq == 0) ssq[(size_t)row * 16 + u.pn * 4 + wc] = q;
.LBB0_1893:
	s_lshl_b32 s4, s47, 8
	v_mov_b32_e32 v158, v1
	s_add_i32 s4, s4, s40
	s_lshl_b32 s22, s46, 2
	v_add_u32_e32 v160, s4, v158
	v_ashrrev_i32_e32 v161, 31, v160
	v_lshl_or_b32 v158, s46, 8, v163
	v_lshlrev_b64 v[166:167], 11, v[160:161]
	v_ashrrev_i32_e32 v159, 31, v158
	v_lshl_add_u64 v[166:167], s[14:15], 0, v[166:167]
	v_lshl_add_u64 v[166:167], v[158:159], 1, v[166:167]
	s_ashr_i32 s23, s22, 31
	v_lshlrev_b32_e32 v252, 11, v160
	v_lshl_add_u32 v252, v158, 1, v252
	v_bfe_u32 v253, v190, 4, 1
	v_mul_u32_u24_e32 v253, 24, v253
	v_add_u32_e32 v252, v252, v253
	s_lshl_b32 s88, s39, 2
	v_lshl_add_u32 v189, v160, 6, s88
	v_lshl_add_u32 v189, s22, 2, v189
	global_load_dwordx4 v[204:207], v252, s[14:15]
	global_load_dwordx4 v[208:211], v252, s[14:15] offset:256
	v_add_u32_e32 v253, 0x8000, v252
	global_load_dwordx4 v[212:215], v253, s[14:15]
	global_load_dwordx4 v[216:219], v253, s[14:15] offset:256
	v_add_u32_e32 v253, 0x10000, v252
	global_load_dwordx4 v[220:223], v253, s[14:15]
	global_load_dwordx4 v[224:227], v253, s[14:15] offset:256
	v_add_u32_e32 v253, 0x18000, v252
	global_load_dwordx4 v[228:231], v253, s[14:15]
	global_load_dwordx4 v[232:235], v253, s[14:15] offset:256
	v_add_u32_e32 v253, 0x40000, v252
	global_load_dwordx4 v[236:239], v253, s[14:15]
	global_load_dwordx4 v[240:243], v253, s[14:15] offset:256
	v_add_u32_e32 v253, 0x48000, v252
	global_load_dwordx4 v[244:247], v253, s[14:15]
	global_load_dwordx4 v[248:251], v253, s[14:15] offset:256
	s_waitcnt vmcnt(10)
	v_permlane16_swap_b32_e32 v204, v206
	v_permlane16_swap_b32_e32 v205, v207
	v_permlane16_swap_b32_e32 v208, v210
	v_permlane16_swap_b32_e32 v209, v211
	v_lshlrev_b32_e32 v166, 16, v204
	v_and_b32_e32 v167, 0xffff0000, v204
	v_lshlrev_b32_e32 v168, 16, v205
	v_and_b32_e32 v169, 0xffff0000, v205
	v_lshlrev_b32_e32 v170, 16, v206
	v_and_b32_e32 v171, 0xffff0000, v206
	v_lshlrev_b32_e32 v172, 16, v207
	v_and_b32_e32 v173, 0xffff0000, v207
	v_lshlrev_b32_e32 v174, 16, v208
	v_and_b32_e32 v175, 0xffff0000, v208
	v_lshlrev_b32_e32 v176, 16, v209
	v_and_b32_e32 v177, 0xffff0000, v209
	v_lshlrev_b32_e32 v178, 16, v210
	v_and_b32_e32 v179, 0xffff0000, v210
	v_lshlrev_b32_e32 v180, 16, v211
	v_and_b32_e32 v181, 0xffff0000, v211
	v_pk_add_f32 v[126:127], v[126:127], v[166:167]
	v_pk_add_f32 v[128:129], v[128:129], v[168:169]
	v_pk_add_f32 v[122:123], v[122:123], v[170:171]
	v_pk_add_f32 v[124:125], v[124:125], v[172:173]
	v_pk_add_f32 v[118:119], v[118:119], v[174:175]
	v_pk_add_f32 v[120:121], v[120:121], v[176:177]
	v_pk_add_f32 v[114:115], v[114:115], v[178:179]
	v_pk_add_f32 v[116:117], v[116:117], v[180:181]
	v_add_u32_e32 v253, 0x50000, v252
	global_load_dwordx4 v[204:207], v253, s[14:15]
	global_load_dwordx4 v[208:211], v253, s[14:15] offset:256
	v_cvt_pk_bf16_f32 v166, v126, v127
	v_cvt_pk_bf16_f32 v167, v128, v129
	v_cvt_pk_bf16_f32 v168, v122, v123
	v_cvt_pk_bf16_f32 v169, v124, v125
	v_cvt_pk_bf16_f32 v170, v118, v119
	v_cvt_pk_bf16_f32 v171, v120, v121
	v_cvt_pk_bf16_f32 v172, v114, v115
	v_cvt_pk_bf16_f32 v173, v116, v117
	v_mul_f32_e32 v174, v126, v126
	v_mul_f32_e32 v175, v122, v122
	v_mul_f32_e32 v176, v118, v118
	v_mul_f32_e32 v177, v114, v114
	v_fmac_f32_e32 v174, v127, v127
	v_fmac_f32_e32 v175, v123, v123
	v_fmac_f32_e32 v176, v119, v119
	v_fmac_f32_e32 v177, v115, v115
	v_fmac_f32_e32 v174, v128, v128
	v_fmac_f32_e32 v175, v124, v124
	v_fmac_f32_e32 v176, v120, v120
	v_fmac_f32_e32 v177, v116, v116
	v_fmac_f32_e32 v174, v129, v129
	v_fmac_f32_e32 v175, v125, v125
	v_fmac_f32_e32 v176, v121, v121
	v_fmac_f32_e32 v177, v117, v117
	v_add_f32_e32 v174, v174, v175
	v_add_f32_e32 v176, v176, v177
	v_add_f32_e32 v178, v174, v176
	v_mov_b32_e32 v179, v178
	v_permlane16_swap_b32_e32 v166, v168
	v_permlane16_swap_b32_e32 v167, v169
	v_permlane32_swap_b32_e32 v179, v178
	v_permlane16_swap_b32_e32 v170, v172
	v_permlane16_swap_b32_e32 v171, v173
	global_store_dwordx4 v252, v[166:169], s[14:15] sc1
	global_store_dwordx4 v252, v[170:173], s[14:15] offset:256 sc1
	v_add_f32_e32 v178, v178, v179
	v_mov_b32_e32 v179, v178
	s_nop 0
	s_nop 0
	v_permlane16_swap_b32_e32 v179, v178
	v_add_f32_e32 v178, v178, v179
	s_and_saveexec_b64 s[24:25], s[6:7]
	global_store_dword v189, v178, s[16:17]
	s_or_b64 exec, exec, s[24:25]
	s_waitcnt vmcnt(12)
; __device__ __forceinline__ float bf_lo(unsigned u) { return __uint_as_float(u << 16); }
; __device__ __forceinline__ float bf_hi(unsigned u) { return __uint_as_float(u & 0xffff0000u); }
; __device__ __forceinline__ unsigned pk_bf16(float lo, float hi) { const f32x2 v = {lo, hi}; const bf16x2_t b = __builtin_convertvector(v, bf16x2_t); return __builtin_bit_cast(unsigned, b); }
;     __device__ __forceinline__ void operator()(const f32x4 (&acc)[2][2][4][2], const pg8::Unit& u, int wr, int wc, int fr, int fq) const {
;     ...
;                     for (int bj = 0; bj < 2; ++bj)
; #pragma unroll
;                         for (int n = 0; n < 2; ++n) { const u32x2 w = *(const u32x2*)(XB + off + bj * 128 + n * 16); r4[bj][n] = (f32x4){bf_lo(w.x), bf_hi(w.x), bf_lo(w.y), bf_hi(w.y)}; }
;                 }
; #pragma unroll
;                 for (int bj = 0; bj < 2; ++bj)
; #pragma unroll
;                     for (int n = 0; n < 2; ++n) { const f32x4 x4 = r4[bj][n] + acc[ai][bj][m][n];
;                         q += (x4[0] * x4[0] + x4[1] * x4[1]) + (x4[2] * x4[2] + x4[3] * x4[3]);
;                         u32x2 w; w.x = pk_bf16(x4[0], x4[1]); w.y = pk_bf16(x4[2], x4[3]); *(u32x2*)(XB + off + bj * 128 + n * 16) = w; }
;                 q += __shfl_xor(q, 16); q += __shfl_xor(q, 32);
;                 if (fq == 0) ssq[(size_t)row * 16 + u.pn * 4 + wc] = q;
	v_permlane16_swap_b32_e32 v212, v214
	v_permlane16_swap_b32_e32 v213, v215
	v_permlane16_swap_b32_e32 v216, v218
	v_permlane16_swap_b32_e32 v217, v219
	v_lshlrev_b32_e32 v166, 16, v212
	v_and_b32_e32 v167, 0xffff0000, v212
	v_lshlrev_b32_e32 v168, 16, v213
	v_and_b32_e32 v169, 0xffff0000, v213
	v_lshlrev_b32_e32 v170, 16, v214
	v_and_b32_e32 v171, 0xffff0000, v214
	v_lshlrev_b32_e32 v172, 16, v215
	v_and_b32_e32 v173, 0xffff0000, v215
	v_lshlrev_b32_e32 v174, 16, v216
	v_and_b32_e32 v175, 0xffff0000, v216
	v_lshlrev_b32_e32 v176, 16, v217
	v_and_b32_e32 v177, 0xffff0000, v217
	v_lshlrev_b32_e32 v178, 16, v218
	v_and_b32_e32 v179, 0xffff0000, v218
	v_lshlrev_b32_e32 v180, 16, v219
	v_and_b32_e32 v181, 0xffff0000, v219
	v_pk_add_f32 v[110:111], v[110:111], v[166:167]
	v_pk_add_f32 v[112:113], v[112:113], v[168:169]
	v_pk_add_f32 v[106:107], v[106:107], v[170:171]
	v_pk_add_f32 v[108:109], v[108:109], v[172:173]
	v_pk_add_f32 v[102:103], v[102:103], v[174:175]
	v_pk_add_f32 v[104:105], v[104:105], v[176:177]
	v_pk_add_f32 v[98:99], v[98:99], v[178:179]
	v_pk_add_f32 v[100:101], v[100:101], v[180:181]
	v_add_u32_e32 v253, 0x58000, v252
	global_load_dwordx4 v[212:215], v253, s[14:15]
	global_load_dwordx4 v[216:219], v253, s[14:15] offset:256
	v_cvt_pk_bf16_f32 v166, v110, v111
	v_cvt_pk_bf16_f32 v167, v112, v113
	v_cvt_pk_bf16_f32 v168, v106, v107
	v_cvt_pk_bf16_f32 v169, v108, v109
	v_cvt_pk_bf16_f32 v170, v102, v103
	v_cvt_pk_bf16_f32 v171, v104, v105
	v_cvt_pk_bf16_f32 v172, v98, v99
	v_cvt_pk_bf16_f32 v173, v100, v101
	v_mul_f32_e32 v174, v110, v110
	v_mul_f32_e32 v175, v106, v106
	v_mul_f32_e32 v176, v102, v102
	v_mul_f32_e32 v177, v98, v98
	v_fmac_f32_e32 v174, v111, v111
	v_fmac_f32_e32 v175, v107, v107
	v_fmac_f32_e32 v176, v103, v103
	v_fmac_f32_e32 v177, v99, v99
	v_fmac_f32_e32 v174, v112, v112
	v_fmac_f32_e32 v175, v108, v108
	v_fmac_f32_e32 v176, v104, v104
	v_fmac_f32_e32 v177, v100, v100
	v_fmac_f32_e32 v174, v113, v113
	v_fmac_f32_e32 v175, v109, v109
	v_fmac_f32_e32 v176, v105, v105
	v_fmac_f32_e32 v177, v101, v101
	v_add_f32_e32 v174, v174, v175
	v_add_f32_e32 v176, v176, v177
	v_add_f32_e32 v178, v174, v176
	v_mov_b32_e32 v179, v178
	v_permlane16_swap_b32_e32 v166, v168
	v_permlane16_swap_b32_e32 v167, v169
	v_permlane32_swap_b32_e32 v179, v178
	v_permlane16_swap_b32_e32 v170, v172
	v_permlane16_swap_b32_e32 v171, v173
	v_add_u32_e32 v253, 0x8000, v252
	global_store_dwordx4 v253, v[166:169], s[14:15] sc1
	global_store_dwordx4 v253, v[170:173], s[14:15] offset:256 sc1
	v_add_f32_e32 v178, v178, v179
	v_mov_b32_e32 v179, v178
	s_nop 0
	s_nop 0
	v_permlane16_swap_b32_e32 v179, v178
	v_add_f32_e32 v178, v178, v179
	s_and_saveexec_b64 s[24:25], s[6:7]
	global_store_dword v189, v178, s[16:17] offset:1024
	s_or_b64 exec, exec, s[24:25]
	s_waitcnt vmcnt(14)
	v_permlane16_swap_b32_e32 v220, v222
	v_permlane16_swap_b32_e32 v221, v223
	v_permlane16_swap_b32_e32 v224, v226
	v_permlane16_swap_b32_e32 v225, v227
	v_lshlrev_b32_e32 v166, 16, v220
	v_and_b32_e32 v167, 0xffff0000, v220
	v_lshlrev_b32_e32 v168, 16, v221
	v_and_b32_e32 v169, 0xffff0000, v221
	v_lshlrev_b32_e32 v170, 16, v222
	v_and_b32_e32 v171, 0xffff0000, v222
	v_lshlrev_b32_e32 v172, 16, v223
	v_and_b32_e32 v173, 0xffff0000, v223
	v_lshlrev_b32_e32 v174, 16, v224
	v_and_b32_e32 v175, 0xffff0000, v224
	v_lshlrev_b32_e32 v176, 16, v225
	v_and_b32_e32 v177, 0xffff0000, v225
	v_lshlrev_b32_e32 v178, 16, v226
	v_and_b32_e32 v179, 0xffff0000, v226
	v_lshlrev_b32_e32 v180, 16, v227
	v_and_b32_e32 v181, 0xffff0000, v227
	v_pk_add_f32 v[94:95], v[94:95], v[166:167]
	v_pk_add_f32 v[96:97], v[96:97], v[168:169]
	v_pk_add_f32 v[90:91], v[90:91], v[170:171]
	v_pk_add_f32 v[92:93], v[92:93], v[172:173]
	v_pk_add_f32 v[86:87], v[86:87], v[174:175]
	v_pk_add_f32 v[88:89], v[88:89], v[176:177]
	v_pk_add_f32 v[82:83], v[82:83], v[178:179]
	v_pk_add_f32 v[84:85], v[84:85], v[180:181]
	v_cvt_pk_bf16_f32 v166, v94, v95
	v_cvt_pk_bf16_f32 v167, v96, v97
	v_cvt_pk_bf16_f32 v168, v90, v91
	v_cvt_pk_bf16_f32 v169, v92, v93
	v_cvt_pk_bf16_f32 v170, v86, v87
	v_cvt_pk_bf16_f32 v171, v88, v89
	v_cvt_pk_bf16_f32 v172, v82, v83
	v_cvt_pk_bf16_f32 v173, v84, v85
	v_mul_f32_e32 v174, v94, v94
	v_mul_f32_e32 v175, v90, v90
	v_mul_f32_e32 v176, v86, v86
	v_mul_f32_e32 v177, v82, v82
	v_fmac_f32_e32 v174, v95, v95
	v_fmac_f32_e32 v175, v91, v91
	v_fmac_f32_e32 v176, v87, v87
	v_fmac_f32_e32 v177, v83, v83
	v_fmac_f32_e32 v174, v96, v96
	v_fmac_f32_e32 v175, v92, v92
	v_fmac_f32_e32 v176, v88, v88
	v_fmac_f32_e32 v177, v84, v84
	v_fmac_f32_e32 v174, v97, v97
	v_fmac_f32_e32 v175, v93, v93
	v_fmac_f32_e32 v176, v89, v89
	v_fmac_f32_e32 v177, v85, v85
	v_add_f32_e32 v174, v174, v175
	v_add_f32_e32 v176, v176, v177
	v_add_f32_e32 v178, v174, v176
	v_mov_b32_e32 v179, v178
	v_permlane16_swap_b32_e32 v166, v168
	v_permlane16_swap_b32_e32 v167, v169
	v_permlane32_swap_b32_e32 v179, v178
	v_permlane16_swap_b32_e32 v170, v172
	v_permlane16_swap_b32_e32 v171, v173
	v_add_u32_e32 v253, 0x10000, v252
	global_store_dwordx4 v253, v[166:169], s[14:15] sc1
	global_store_dwordx4 v253, v[170:173], s[14:15] offset:256 sc1
	v_add_f32_e32 v178, v178, v179
	v_mov_b32_e32 v179, v178
	s_nop 0
	s_nop 0
	v_permlane16_swap_b32_e32 v179, v178
	v_add_f32_e32 v178, v178, v179
	s_and_saveexec_b64 s[24:25], s[6:7]
	global_store_dword v189, v178, s[16:17] offset:2048
	s_or_b64 exec, exec, s[24:25]
	s_waitcnt vmcnt(14)
; __device__ __forceinline__ float bf_lo(unsigned u) { return __uint_as_float(u << 16); }
; __device__ __forceinline__ float bf_hi(unsigned u) { return __uint_as_float(u & 0xffff0000u); }
; __device__ __forceinline__ unsigned pk_bf16(float lo, float hi) { const f32x2 v = {lo, hi}; const bf16x2_t b = __builtin_convertvector(v, bf16x2_t); return __builtin_bit_cast(unsigned, b); }
;     __device__ __forceinline__ void operator()(const f32x4 (&acc)[2][2][4][2], const pg8::Unit& u, int wr, int wc, int fr, int fq) const {
;     ...
;                     for (int bj = 0; bj < 2; ++bj)
; #pragma unroll
;                         for (int n = 0; n < 2; ++n) { const u32x2 w = *(const u32x2*)(XB + off + bj * 128 + n * 16); r4[bj][n] = (f32x4){bf_lo(w.x), bf_hi(w.x), bf_lo(w.y), bf_hi(w.y)}; }
;                 }
; #pragma unroll
;                 for (int bj = 0; bj < 2; ++bj)
; #pragma unroll
;                     for (int n = 0; n < 2; ++n) { const f32x4 x4 = r4[bj][n] + acc[ai][bj][m][n];
;                         q += (x4[0] * x4[0] + x4[1] * x4[1]) + (x4[2] * x4[2] + x4[3] * x4[3]);
;                         u32x2 w; w.x = pk_bf16(x4[0], x4[1]); w.y = pk_bf16(x4[2], x4[3]); *(u32x2*)(XB + off + bj * 128 + n * 16) = w; }
;                 q += __shfl_xor(q, 16); q += __shfl_xor(q, 32);
;                 if (fq == 0) ssq[(size_t)row * 16 + u.pn * 4 + wc] = q;
	v_permlane16_swap_b32_e32 v228, v230
	v_permlane16_swap_b32_e32 v229, v231
	v_permlane16_swap_b32_e32 v232, v234
	v_permlane16_swap_b32_e32 v233, v235
	v_lshlrev_b32_e32 v166, 16, v228
	v_and_b32_e32 v167, 0xffff0000, v228
	v_lshlrev_b32_e32 v168, 16, v229
	v_and_b32_e32 v169, 0xffff0000, v229
	v_lshlrev_b32_e32 v170, 16, v230
	v_and_b32_e32 v171, 0xffff0000, v230
	v_lshlrev_b32_e32 v172, 16, v231
	v_and_b32_e32 v173, 0xffff0000, v231
	v_lshlrev_b32_e32 v174, 16, v232
	v_and_b32_e32 v175, 0xffff0000, v232
	v_lshlrev_b32_e32 v176, 16, v233
	v_and_b32_e32 v177, 0xffff0000, v233
	v_lshlrev_b32_e32 v178, 16, v234
	v_and_b32_e32 v179, 0xffff0000, v234
	v_lshlrev_b32_e32 v180, 16, v235
	v_and_b32_e32 v181, 0xffff0000, v235
	v_pk_add_f32 v[78:79], v[78:79], v[166:167]
	v_pk_add_f32 v[80:81], v[80:81], v[168:169]
	v_pk_add_f32 v[74:75], v[74:75], v[170:171]
	v_pk_add_f32 v[76:77], v[76:77], v[172:173]
	v_pk_add_f32 v[70:71], v[70:71], v[174:175]
	v_pk_add_f32 v[72:73], v[72:73], v[176:177]
	v_pk_add_f32 v[66:67], v[66:67], v[178:179]
	v_pk_add_f32 v[68:69], v[68:69], v[180:181]
	v_cvt_pk_bf16_f32 v166, v78, v79
	v_cvt_pk_bf16_f32 v167, v80, v81
	v_cvt_pk_bf16_f32 v168, v74, v75
	v_cvt_pk_bf16_f32 v169, v76, v77
	v_cvt_pk_bf16_f32 v170, v70, v71
	v_cvt_pk_bf16_f32 v171, v72, v73
	v_cvt_pk_bf16_f32 v172, v66, v67
	v_cvt_pk_bf16_f32 v173, v68, v69
	v_mul_f32_e32 v174, v78, v78
	v_mul_f32_e32 v175, v74, v74
	v_mul_f32_e32 v176, v70, v70
	v_mul_f32_e32 v177, v66, v66
	v_fmac_f32_e32 v174, v79, v79
	v_fmac_f32_e32 v175, v75, v75
	v_fmac_f32_e32 v176, v71, v71
	v_fmac_f32_e32 v177, v67, v67
	v_fmac_f32_e32 v174, v80, v80
	v_fmac_f32_e32 v175, v76, v76
	v_fmac_f32_e32 v176, v72, v72
	v_fmac_f32_e32 v177, v68, v68
	v_fmac_f32_e32 v174, v81, v81
	v_fmac_f32_e32 v175, v77, v77
	v_fmac_f32_e32 v176, v73, v73
	v_fmac_f32_e32 v177, v69, v69
	v_add_f32_e32 v174, v174, v175
	v_add_f32_e32 v176, v176, v177
	v_add_f32_e32 v178, v174, v176
	v_mov_b32_e32 v179, v178
	v_permlane16_swap_b32_e32 v166, v168
	v_permlane16_swap_b32_e32 v167, v169
	v_permlane32_swap_b32_e32 v179, v178
	v_permlane16_swap_b32_e32 v170, v172
	v_permlane16_swap_b32_e32 v171, v173
	v_add_u32_e32 v253, 0x18000, v252
	global_store_dwordx4 v253, v[166:169], s[14:15] sc1
	global_store_dwordx4 v253, v[170:173], s[14:15] offset:256 sc1
	v_add_f32_e32 v178, v178, v179
	v_mov_b32_e32 v179, v178
	s_nop 0
	s_nop 0
	v_permlane16_swap_b32_e32 v179, v178
	v_add_f32_e32 v178, v178, v179
	s_and_saveexec_b64 s[24:25], s[6:7]
	global_store_dword v189, v178, s[16:17] offset:3072
	s_or_b64 exec, exec, s[24:25]
	s_waitcnt vmcnt(14)
	v_permlane16_swap_b32_e32 v236, v238
	v_permlane16_swap_b32_e32 v237, v239
	v_permlane16_swap_b32_e32 v240, v242
	v_permlane16_swap_b32_e32 v241, v243
	v_lshlrev_b32_e32 v166, 16, v236
	v_and_b32_e32 v167, 0xffff0000, v236
	v_lshlrev_b32_e32 v168, 16, v237
	v_and_b32_e32 v169, 0xffff0000, v237
	v_lshlrev_b32_e32 v170, 16, v238
	v_and_b32_e32 v171, 0xffff0000, v238
	v_lshlrev_b32_e32 v172, 16, v239
	v_and_b32_e32 v173, 0xffff0000, v239
	v_lshlrev_b32_e32 v174, 16, v240
	v_and_b32_e32 v175, 0xffff0000, v240
	v_lshlrev_b32_e32 v176, 16, v241
	v_and_b32_e32 v177, 0xffff0000, v241
	v_lshlrev_b32_e32 v178, 16, v242
	v_and_b32_e32 v179, 0xffff0000, v242
	v_lshlrev_b32_e32 v180, 16, v243
	v_and_b32_e32 v181, 0xffff0000, v243
	v_pk_add_f32 v[62:63], v[62:63], v[166:167]
	v_pk_add_f32 v[64:65], v[64:65], v[168:169]
	v_pk_add_f32 v[58:59], v[58:59], v[170:171]
	v_pk_add_f32 v[60:61], v[60:61], v[172:173]
	v_pk_add_f32 v[54:55], v[54:55], v[174:175]
	v_pk_add_f32 v[56:57], v[56:57], v[176:177]
	v_pk_add_f32 v[50:51], v[50:51], v[178:179]
	v_pk_add_f32 v[52:53], v[52:53], v[180:181]
	v_cvt_pk_bf16_f32 v166, v62, v63
	v_cvt_pk_bf16_f32 v167, v64, v65
	v_cvt_pk_bf16_f32 v168, v58, v59
	v_cvt_pk_bf16_f32 v169, v60, v61
	v_cvt_pk_bf16_f32 v170, v54, v55
	v_cvt_pk_bf16_f32 v171, v56, v57
	v_cvt_pk_bf16_f32 v172, v50, v51
	v_cvt_pk_bf16_f32 v173, v52, v53
	v_mul_f32_e32 v174, v62, v62
	v_mul_f32_e32 v175, v58, v58
	v_mul_f32_e32 v176, v54, v54
	v_mul_f32_e32 v177, v50, v50
	v_fmac_f32_e32 v174, v63, v63
	v_fmac_f32_e32 v175, v59, v59
	v_fmac_f32_e32 v176, v55, v55
	v_fmac_f32_e32 v177, v51, v51
	v_fmac_f32_e32 v174, v64, v64
	v_fmac_f32_e32 v175, v60, v60
	v_fmac_f32_e32 v176, v56, v56
	v_fmac_f32_e32 v177, v52, v52
	v_fmac_f32_e32 v174, v65, v65
	v_fmac_f32_e32 v175, v61, v61
	v_fmac_f32_e32 v176, v57, v57
	v_fmac_f32_e32 v177, v53, v53
	v_add_f32_e32 v174, v174, v175
	v_add_f32_e32 v176, v176, v177
	v_add_f32_e32 v178, v174, v176
	v_mov_b32_e32 v179, v178
	v_permlane16_swap_b32_e32 v166, v168
	v_permlane16_swap_b32_e32 v167, v169
	v_permlane32_swap_b32_e32 v179, v178
	v_permlane16_swap_b32_e32 v170, v172
	v_permlane16_swap_b32_e32 v171, v173
	v_add_u32_e32 v253, 0x40000, v252
	global_store_dwordx4 v253, v[166:169], s[14:15] sc1
	global_store_dwordx4 v253, v[170:173], s[14:15] offset:256 sc1
	v_add_f32_e32 v178, v178, v179
	v_mov_b32_e32 v179, v178
	v_add_u32_e32 v189, 0x2000, v189
	s_nop 0
	v_permlane16_swap_b32_e32 v179, v178
	v_add_f32_e32 v178, v178, v179
	s_and_saveexec_b64 s[24:25], s[6:7]
	global_store_dword v189, v178, s[16:17]
	s_or_b64 exec, exec, s[24:25]
	s_waitcnt vmcnt(14)
; __device__ __forceinline__ float bf_lo(unsigned u) { return __uint_as_float(u << 16); }
; __device__ __forceinline__ float bf_hi(unsigned u) { return __uint_as_float(u & 0xffff0000u); }
; __device__ __forceinline__ unsigned pk_bf16(float lo, float hi) { const f32x2 v = {lo, hi}; const bf16x2_t b = __builtin_convertvector(v, bf16x2_t); return __builtin_bit_cast(unsigned, b); }
;     __device__ __forceinline__ void operator()(const f32x4 (&acc)[2][2][4][2], const pg8::Unit& u, int wr, int wc, int fr, int fq) const {
;     ...
;                     for (int bj = 0; bj < 2; ++bj)
; #pragma unroll
;                         for (int n = 0; n < 2; ++n) { const u32x2 w = *(const u32x2*)(XB + off + bj * 128 + n * 16); r4[bj][n] = (f32x4){bf_lo(w.x), bf_hi(w.x), bf_lo(w.y), bf_hi(w.y)}; }
;                 }
; #pragma unroll
;                 for (int bj = 0; bj < 2; ++bj)
; #pragma unroll
;                     for (int n = 0; n < 2; ++n) { const f32x4 x4 = r4[bj][n] + acc[ai][bj][m][n];
;                         q += (x4[0] * x4[0] + x4[1] * x4[1]) + (x4[2] * x4[2] + x4[3] * x4[3]);
;                         u32x2 w; w.x = pk_bf16(x4[0], x4[1]); w.y = pk_bf16(x4[2], x4[3]); *(u32x2*)(XB + off + bj * 128 + n * 16) = w; }
;                 q += __shfl_xor(q, 16); q += __shfl_xor(q, 32);
;                 if (fq == 0) ssq[(size_t)row * 16 + u.pn * 4 + wc] = q;
	v_permlane16_swap_b32_e32 v244, v246
	v_permlane16_swap_b32_e32 v245, v247
	v_permlane16_swap_b32_e32 v248, v250
	v_permlane16_swap_b32_e32 v249, v251
	v_lshlrev_b32_e32 v166, 16, v244
	v_and_b32_e32 v167, 0xffff0000, v244
	v_lshlrev_b32_e32 v168, 16, v245
	v_and_b32_e32 v169, 0xffff0000, v245
	v_lshlrev_b32_e32 v170, 16, v246
	v_and_b32_e32 v171, 0xffff0000, v246
	v_lshlrev_b32_e32 v172, 16, v247
	v_and_b32_e32 v173, 0xffff0000, v247
	v_lshlrev_b32_e32 v174, 16, v248
	v_and_b32_e32 v175, 0xffff0000, v248
	v_lshlrev_b32_e32 v176, 16, v249
	v_and_b32_e32 v177, 0xffff0000, v249
	v_lshlrev_b32_e32 v178, 16, v250
	v_and_b32_e32 v179, 0xffff0000, v250
	v_lshlrev_b32_e32 v180, 16, v251
	v_and_b32_e32 v181, 0xffff0000, v251
	v_pk_add_f32 v[46:47], v[46:47], v[166:167]
	v_pk_add_f32 v[48:49], v[48:49], v[168:169]
	v_pk_add_f32 v[42:43], v[42:43], v[170:171]
	v_pk_add_f32 v[44:45], v[44:45], v[172:173]
	v_pk_add_f32 v[38:39], v[38:39], v[174:175]
	v_pk_add_f32 v[40:41], v[40:41], v[176:177]
	v_pk_add_f32 v[34:35], v[34:35], v[178:179]
	v_pk_add_f32 v[36:37], v[36:37], v[180:181]
	v_cvt_pk_bf16_f32 v166, v46, v47
	v_cvt_pk_bf16_f32 v167, v48, v49
	v_cvt_pk_bf16_f32 v168, v42, v43
	v_cvt_pk_bf16_f32 v169, v44, v45
	v_cvt_pk_bf16_f32 v170, v38, v39
	v_cvt_pk_bf16_f32 v171, v40, v41
	v_cvt_pk_bf16_f32 v172, v34, v35
	v_cvt_pk_bf16_f32 v173, v36, v37
	v_mul_f32_e32 v174, v46, v46
	v_mul_f32_e32 v175, v42, v42
	v_mul_f32_e32 v176, v38, v38
	v_mul_f32_e32 v177, v34, v34
	v_fmac_f32_e32 v174, v47, v47
	v_fmac_f32_e32 v175, v43, v43
	v_fmac_f32_e32 v176, v39, v39
	v_fmac_f32_e32 v177, v35, v35
	v_fmac_f32_e32 v174, v48, v48
	v_fmac_f32_e32 v175, v44, v44
	v_fmac_f32_e32 v176, v40, v40
	v_fmac_f32_e32 v177, v36, v36
	v_fmac_f32_e32 v174, v49, v49
	v_fmac_f32_e32 v175, v45, v45
	v_fmac_f32_e32 v176, v41, v41
	v_fmac_f32_e32 v177, v37, v37
	v_add_f32_e32 v174, v174, v175
	v_add_f32_e32 v176, v176, v177
	v_add_f32_e32 v178, v174, v176
	v_mov_b32_e32 v179, v178
	v_permlane16_swap_b32_e32 v166, v168
	v_permlane16_swap_b32_e32 v167, v169
	v_permlane32_swap_b32_e32 v179, v178
	v_permlane16_swap_b32_e32 v170, v172
	v_permlane16_swap_b32_e32 v171, v173
	v_add_u32_e32 v253, 0x48000, v252
	global_store_dwordx4 v253, v[166:169], s[14:15] sc1
	global_store_dwordx4 v253, v[170:173], s[14:15] offset:256 sc1
	v_add_f32_e32 v178, v178, v179
	v_mov_b32_e32 v179, v178
	s_nop 0
	s_nop 0
	v_permlane16_swap_b32_e32 v179, v178
	v_add_f32_e32 v178, v178, v179
	s_and_saveexec_b64 s[24:25], s[6:7]
	global_store_dword v189, v178, s[16:17] offset:1024
	s_or_b64 exec, exec, s[24:25]
	s_waitcnt vmcnt(14)
; __device__ __forceinline__ float bf_lo(unsigned u) { return __uint_as_float(u << 16); }
; __device__ __forceinline__ float bf_hi(unsigned u) { return __uint_as_float(u & 0xffff0000u); }
; __device__ __forceinline__ unsigned pk_bf16(float lo, float hi) { const f32x2 v = {lo, hi}; const bf16x2_t b = __builtin_convertvector(v, bf16x2_t); return __builtin_bit_cast(unsigned, b); }
;     __device__ __forceinline__ void operator()(const f32x4 (&acc)[2][2][4][2], const pg8::Unit& u, int wr, int wc, int fr, int fq) const {
;     ...
;                     for (int bj = 0; bj < 2; ++bj)
; #pragma unroll
;                         for (int n = 0; n < 2; ++n) { const u32x2 w = *(const u32x2*)(XB + off + bj * 128 + n * 16); r4[bj][n] = (f32x4){bf_lo(w.x), bf_hi(w.x), bf_lo(w.y), bf_hi(w.y)}; }
;                 }
; #pragma unroll
;                 for (int bj = 0; bj < 2; ++bj)
; #pragma unroll
;                     for (int n = 0; n < 2; ++n) { const f32x4 x4 = r4[bj][n] + acc[ai][bj][m][n];
;                         q += (x4[0] * x4[0] + x4[1] * x4[1]) + (x4[2] * x4[2] + x4[3] * x4[3]);
;                         u32x2 w; w.x = pk_bf16(x4[0], x4[1]); w.y = pk_bf16(x4[2], x4[3]); *(u32x2*)(XB + off + bj * 128 + n * 16) = w; }
;                 q += __shfl_xor(q, 16); q += __shfl_xor(q, 32);
;                 if (fq == 0) ssq[(size_t)row * 16 + u.pn * 4 + wc] = q;
	v_permlane16_swap_b32_e32 v204, v206
	v_permlane16_swap_b32_e32 v205, v207
	v_permlane16_swap_b32_e32 v208, v210
	v_permlane16_swap_b32_e32 v209, v211
	v_lshlrev_b32_e32 v166, 16, v204
	v_and_b32_e32 v167, 0xffff0000, v204
	v_lshlrev_b32_e32 v168, 16, v205
	v_and_b32_e32 v169, 0xffff0000, v205
	v_lshlrev_b32_e32 v170, 16, v206
	v_and_b32_e32 v171, 0xffff0000, v206
	v_lshlrev_b32_e32 v172, 16, v207
	v_and_b32_e32 v173, 0xffff0000, v207
	v_lshlrev_b32_e32 v174, 16, v208
	v_and_b32_e32 v175, 0xffff0000, v208
	v_lshlrev_b32_e32 v176, 16, v209
	v_and_b32_e32 v177, 0xffff0000, v209
	v_lshlrev_b32_e32 v178, 16, v210
	v_and_b32_e32 v179, 0xffff0000, v210
	v_lshlrev_b32_e32 v180, 16, v211
	v_and_b32_e32 v181, 0xffff0000, v211
	v_pk_add_f32 v[30:31], v[30:31], v[166:167]
	v_pk_add_f32 v[32:33], v[32:33], v[168:169]
	v_pk_add_f32 v[26:27], v[26:27], v[170:171]
	v_pk_add_f32 v[28:29], v[28:29], v[172:173]
	v_pk_add_f32 v[22:23], v[22:23], v[174:175]
	v_pk_add_f32 v[24:25], v[24:25], v[176:177]
	v_pk_add_f32 v[18:19], v[18:19], v[178:179]
	v_pk_add_f32 v[20:21], v[20:21], v[180:181]
	v_cvt_pk_bf16_f32 v166, v30, v31
	v_cvt_pk_bf16_f32 v167, v32, v33
	v_cvt_pk_bf16_f32 v168, v26, v27
	v_cvt_pk_bf16_f32 v169, v28, v29
	v_cvt_pk_bf16_f32 v170, v22, v23
	v_cvt_pk_bf16_f32 v171, v24, v25
	v_cvt_pk_bf16_f32 v172, v18, v19
	v_cvt_pk_bf16_f32 v173, v20, v21
	v_mul_f32_e32 v174, v30, v30
	v_mul_f32_e32 v175, v26, v26
	v_mul_f32_e32 v176, v22, v22
	v_mul_f32_e32 v177, v18, v18
	v_fmac_f32_e32 v174, v31, v31
	v_fmac_f32_e32 v175, v27, v27
	v_fmac_f32_e32 v176, v23, v23
	v_fmac_f32_e32 v177, v19, v19
	v_fmac_f32_e32 v174, v32, v32
	v_fmac_f32_e32 v175, v28, v28
	v_fmac_f32_e32 v176, v24, v24
	v_fmac_f32_e32 v177, v20, v20
	v_fmac_f32_e32 v174, v33, v33
	v_fmac_f32_e32 v175, v29, v29
	v_fmac_f32_e32 v176, v25, v25
	v_fmac_f32_e32 v177, v21, v21
	v_add_f32_e32 v174, v174, v175
	v_add_f32_e32 v176, v176, v177
	v_add_f32_e32 v178, v174, v176
	v_mov_b32_e32 v179, v178
	v_permlane16_swap_b32_e32 v166, v168
	v_permlane16_swap_b32_e32 v167, v169
	v_permlane32_swap_b32_e32 v179, v178
	v_permlane16_swap_b32_e32 v170, v172
	v_permlane16_swap_b32_e32 v171, v173
	v_add_u32_e32 v253, 0x50000, v252
	global_store_dwordx4 v253, v[166:169], s[14:15] sc1
	global_store_dwordx4 v253, v[170:173], s[14:15] offset:256 sc1
	v_add_f32_e32 v178, v178, v179
	v_mov_b32_e32 v179, v178
	s_nop 0
	s_nop 0
	v_permlane16_swap_b32_e32 v179, v178
	v_add_f32_e32 v178, v178, v179
	s_and_saveexec_b64 s[24:25], s[6:7]
	global_store_dword v189, v178, s[16:17] offset:2048
	s_or_b64 exec, exec, s[24:25]
	s_waitcnt vmcnt(12)
	v_permlane16_swap_b32_e32 v212, v214
	v_permlane16_swap_b32_e32 v213, v215
	v_permlane16_swap_b32_e32 v216, v218
	v_permlane16_swap_b32_e32 v217, v219
	v_lshlrev_b32_e32 v166, 16, v212
	v_and_b32_e32 v167, 0xffff0000, v212
	v_lshlrev_b32_e32 v168, 16, v213
	v_and_b32_e32 v169, 0xffff0000, v213
	v_lshlrev_b32_e32 v170, 16, v214
	v_and_b32_e32 v171, 0xffff0000, v214
	v_lshlrev_b32_e32 v172, 16, v215
	v_and_b32_e32 v173, 0xffff0000, v215
	v_lshlrev_b32_e32 v174, 16, v216
	v_and_b32_e32 v175, 0xffff0000, v216
	v_lshlrev_b32_e32 v176, 16, v217
	v_and_b32_e32 v177, 0xffff0000, v217
	v_lshlrev_b32_e32 v178, 16, v218
	v_and_b32_e32 v179, 0xffff0000, v218
	v_lshlrev_b32_e32 v180, 16, v219
	v_and_b32_e32 v181, 0xffff0000, v219
	v_pk_add_f32 v[14:15], v[14:15], v[166:167]
	v_pk_add_f32 v[16:17], v[16:17], v[168:169]
	v_pk_add_f32 v[10:11], v[10:11], v[170:171]
	v_pk_add_f32 v[12:13], v[12:13], v[172:173]
	v_pk_add_f32 v[6:7], v[6:7], v[174:175]
	v_pk_add_f32 v[8:9], v[8:9], v[176:177]
	v_pk_add_f32 v[2:3], v[2:3], v[178:179]
	v_pk_add_f32 v[4:5], v[4:5], v[180:181]
	v_cvt_pk_bf16_f32 v166, v14, v15
	v_cvt_pk_bf16_f32 v167, v16, v17
	v_cvt_pk_bf16_f32 v168, v10, v11
	v_cvt_pk_bf16_f32 v169, v12, v13
	v_cvt_pk_bf16_f32 v170, v6, v7
	v_cvt_pk_bf16_f32 v171, v8, v9
	v_cvt_pk_bf16_f32 v172, v2, v3
	v_cvt_pk_bf16_f32 v173, v4, v5
	v_mul_f32_e32 v174, v14, v14
	v_mul_f32_e32 v175, v10, v10
	v_mul_f32_e32 v176, v6, v6
	v_mul_f32_e32 v177, v2, v2
	v_fmac_f32_e32 v174, v15, v15
	v_fmac_f32_e32 v175, v11, v11
	v_fmac_f32_e32 v176, v7, v7
	v_fmac_f32_e32 v177, v3, v3
	v_fmac_f32_e32 v174, v16, v16
	v_fmac_f32_e32 v175, v12, v12
	v_fmac_f32_e32 v176, v8, v8
	v_fmac_f32_e32 v177, v4, v4
	v_fmac_f32_e32 v174, v17, v17
	v_fmac_f32_e32 v175, v13, v13
	v_fmac_f32_e32 v176, v9, v9
	v_fmac_f32_e32 v177, v5, v5
	v_add_f32_e32 v174, v174, v175
	v_add_f32_e32 v176, v176, v177
	v_add_f32_e32 v178, v174, v176
	v_mov_b32_e32 v179, v178
	v_permlane16_swap_b32_e32 v166, v168
	v_permlane16_swap_b32_e32 v167, v169
	v_permlane32_swap_b32_e32 v179, v178
	v_permlane16_swap_b32_e32 v170, v172
	v_permlane16_swap_b32_e32 v171, v173
	v_add_u32_e32 v253, 0x58000, v252
	global_store_dwordx4 v253, v[166:169], s[14:15] sc1
	global_store_dwordx4 v253, v[170:173], s[14:15] offset:256 sc1
	v_add_f32_e32 v178, v178, v179
	v_mov_b32_e32 v179, v178
	s_nop 0
	s_nop 0
	v_permlane16_swap_b32_e32 v179, v178
	v_add_f32_e32 v178, v178, v179
	s_and_saveexec_b64 s[24:25], s[6:7]
	global_store_dword v189, v178, s[16:17] offset:3072
	s_or_b64 exec, exec, s[24:25]
